# v67 + P0 RMSNorm loop: norm gains loaded once before the loop instead of four serialized loads + vmcnt(0) per iteration
# speedup vs baseline: 1.0105x; 1.0038x over previous
.LBB0_47:
	s_or_b64 exec, exec, s[8:9]
	s_load_dword s3, s[0:1], 0x68
	s_cmpk_gt_i32 s12, 0x3fff
	v_mbcnt_lo_u32_b32 v205, -1, 0
	v_cmp_eq_u32_e64 s[0:1], 0, v204
	s_cbranch_scc1 .LBB0_58
	v_mbcnt_hi_u32_b32 v2, -1, v205
	v_and_b32_e32 v1, 64, v2
	s_ashr_i32 s7, s6, 31
	v_add_u32_e32 v3, 64, v1
	v_xor_b32_e32 v1, 1, v2
	s_lshl_b32 s4, s54, 4
	s_mul_i32 s8, s54, 24
	s_ashr_i32 s13, s12, 31
	v_cmp_lt_i32_e32 vcc, v1, v3
	v_xor_b32_e32 v4, 2, v2
	s_ashr_i32 s5, s4, 31
	s_ashr_i32 s9, s8, 31
	s_lshl_b32 s18, s54, 5
	s_lshl_b64 s[20:21], s[6:7], 12
	s_lshl_b64 s[10:11], s[6:7], 11
	s_lshl_b64 s[14:15], s[12:13], 2
	v_cndmask_b32_e32 v1, v2, v1, vcc
	v_cmp_lt_i32_e32 vcc, v4, v3
	s_add_u32 s46, s14, 0x1980000
	s_addc_u32 s47, s15, 0
	v_cndmask_b32_e32 v4, v2, v4, vcc
	s_ashr_i32 s19, s18, 31
	v_lshlrev_b32_e32 v83, 2, v4
	v_xor_b32_e32 v4, 4, v2
	s_lshl_b64 s[28:29], s[18:19], 2
	s_lshl_b64 s[14:15], s[6:7], 2
	v_cmp_lt_i32_e32 vcc, v4, v3
	s_add_u32 s48, s46, s14
	s_addc_u32 s49, s47, s15
	v_cndmask_b32_e32 v4, v2, v4, vcc
	s_lshl_b64 s[4:5], s[4:5], 2
	v_lshlrev_b32_e32 v85, 2, v4
	v_xor_b32_e32 v4, 8, v2
	s_add_u32 s56, s46, s4
	v_cmp_lt_i32_e32 vcc, v4, v3
	s_addc_u32 s57, s47, s5
	s_lshl_b64 s[4:5], s[8:9], 2
	v_cndmask_b32_e32 v4, v2, v4, vcc
	s_add_u32 s60, s46, s4
	v_lshlrev_b32_e32 v87, 2, v4
	v_xor_b32_e32 v4, 16, v2
	s_addc_u32 s61, s47, s5
	s_lshl_b64 s[4:5], s[12:13], 12
	v_cmp_lt_i32_e32 vcc, v4, v3
	s_add_u32 s4, s36, s4
	v_lshlrev_b32_e32 v66, 4, v204
	v_cndmask_b32_e32 v4, v2, v4, vcc
	v_mov_b32_e32 v67, 0
	s_addc_u32 s5, s37, s5
	v_lshlrev_b32_e32 v88, 2, v4
	v_xor_b32_e32 v4, 32, v2
	v_lshl_add_u64 v[70:71], s[4:5], 0, v[66:67]
	s_lshl_b64 s[36:37], s[18:19], 12
	s_lshl_b64 s[4:5], s[12:13], 11
	s_lshl_b64 s[44:45], s[18:19], 11
	v_cmp_lt_i32_e32 vcc, v4, v3
	s_add_u32 s7, s10, s4
	s_addc_u32 s8, s11, s5
	v_cndmask_b32_e32 v2, v2, v4, vcc
	v_lshlrev_b32_e32 v4, 3, v204
	v_lshlrev_b32_e32 v89, 2, v2
	v_or_b32_e32 v2, s7, v4
	v_mov_b32_e32 v3, s8
	s_mov_b64 s[8:9], 0x2000400
	s_add_u32 s7, s20, s4
	v_lshl_add_u64 v[74:75], v[2:3], 0, s[8:9]
	s_addc_u32 s10, s21, s5
	v_or_b32_e32 v2, s7, v4
	s_mul_hi_i32 s7, s6, 0x1800
	s_mulk_i32 s6, 0x1800
	v_or_b32_e32 v72, s4, v4
	s_add_u32 s4, s6, s4
	v_mov_b32_e32 v73, s5
	v_mov_b32_e32 v3, s10
	s_addc_u32 s5, s7, s5
	v_lshl_add_u64 v[76:77], v[2:3], 0, s[8:9]
	v_or_b32_e32 v2, s4, v4
	v_mov_b32_e32 v3, s5
	v_lshlrev_b32_e32 v1, 2, v1
	v_lshl_add_u64 v[68:69], s[38:39], 0, v[66:67]
	v_lshl_add_u64 v[78:79], v[2:3], 0, s[8:9]
	v_mov_b32_e32 v90, 0x358637bd
	s_mov_b32 s13, 0xf800000
	v_mov_b32_e32 v91, 0x260
	s_movk_i32 s19, 0x7fff
	s_mov_b32 s62, 0xffff0000
	s_brev_b32 s63, 64
	global_load_dwordx4 v[120:123], v[68:69], off
	global_load_dwordx4 v[124:127], v[68:69], off offset:1024
	global_load_dwordx4 v[128:131], v[68:69], off offset:2048
	global_load_dwordx4 v[132:135], v[68:69], off offset:3072
	s_branch .LBB0_50
.LBB0_49:
	s_or_b64 exec, exec, s[4:5]
	v_mov_b64_e32 v[92:93], v[120:121]
	v_mov_b64_e32 v[94:95], v[122:123]
	v_div_scale_f32 v96, s[4:5], v66, v66, 1.0
	v_div_scale_f32 v98, s[4:5], v82, v82, 1.0
	v_rcp_f32_e32 v104, v96
	v_div_scale_f32 v100, s[6:7], v84, v84, 1.0
	v_rcp_f32_e32 v105, v98
	v_div_scale_f32 v102, s[8:9], v86, v86, 1.0
	v_rcp_f32_e32 v106, v100
	v_rcp_f32_e32 v107, v102
	v_fma_f32 v108, -v96, v104, 1.0
	v_div_scale_f32 v97, vcc, 1.0, v66, 1.0
	v_fma_f32 v109, -v98, v105, 1.0
	v_fmac_f32_e32 v104, v108, v104
	v_div_scale_f32 v99, s[4:5], 1.0, v82, 1.0
	v_fma_f32 v110, -v100, v106, 1.0
	v_fmac_f32_e32 v105, v109, v105
	v_mul_f32_e32 v108, v97, v104
	v_div_scale_f32 v101, s[6:7], 1.0, v84, 1.0
	v_fma_f32 v111, -v102, v107, 1.0
	v_fmac_f32_e32 v106, v110, v106
	v_mul_f32_e32 v109, v99, v105
	v_fma_f32 v112, -v96, v108, v97
	v_div_scale_f32 v103, s[8:9], 1.0, v86, 1.0
	v_fmac_f32_e32 v107, v111, v107
	v_mul_f32_e32 v110, v101, v106
	v_fma_f32 v113, -v98, v109, v99
	v_fmac_f32_e32 v108, v112, v104
	v_mul_f32_e32 v111, v103, v107
	v_fma_f32 v114, -v100, v110, v101
	v_fmac_f32_e32 v109, v113, v105
	v_fma_f32 v96, -v96, v108, v97
	v_fma_f32 v115, -v102, v111, v103
	v_fmac_f32_e32 v110, v114, v106
	v_fma_f32 v97, -v98, v109, v99
	v_div_fmas_f32 v96, v96, v104, v108
	s_mov_b64 vcc, s[4:5]
	v_fmac_f32_e32 v111, v115, v107
	v_fma_f32 v98, -v100, v110, v101
	v_div_fixup_f32 v66, v96, v66, 1.0
	v_div_fmas_f32 v96, v97, v105, v109
	s_mov_b64 vcc, s[6:7]
	v_fma_f32 v99, -v102, v111, v103
	v_div_fixup_f32 v82, v96, v82, 1.0
	v_div_fmas_f32 v96, v98, v106, v110
	s_mov_b64 vcc, s[8:9]
	v_div_fixup_f32 v84, v96, v84, 1.0
	v_div_fmas_f32 v96, v99, v107, v111
	v_div_fixup_f32 v86, v96, v86, 1.0
	v_pk_mul_f32 v[58:59], v[58:59], v[86:87] op_sel_hi:[1,0]
	v_pk_mul_f32 v[60:61], v[60:61], v[86:87] op_sel_hi:[1,0]
	v_lshl_add_u64 v[80:81], s[52:53], 0, v[72:73]
	v_pk_mul_f32 v[62:63], v[62:63], v[84:85] op_sel_hi:[1,0]
	v_add_co_u32_e64 v80, s[10:11], s63, v80
	v_pk_mul_f32 v[64:65], v[64:65], v[84:85] op_sel_hi:[1,0]
	s_nop 0
	v_addc_co_u32_e64 v81, s[10:11], 0, v81, s[10:11]
	v_pk_mul_f32 v[54:55], v[54:55], v[82:83] op_sel_hi:[1,0]
	v_pk_mul_f32 v[56:57], v[56:57], v[82:83] op_sel_hi:[1,0]
	v_pk_mul_f32 v[50:51], v[50:51], v[66:67] op_sel_hi:[1,0]
	v_pk_mul_f32 v[52:53], v[52:53], v[66:67] op_sel_hi:[1,0]
	v_pk_mul_f32 v[38:39], v[38:39], v[86:87] op_sel_hi:[1,0]
	v_pk_mul_f32 v[40:41], v[40:41], v[86:87] op_sel_hi:[1,0]
	v_pk_mul_f32 v[42:43], v[42:43], v[84:85] op_sel_hi:[1,0]
	v_pk_mul_f32 v[44:45], v[44:45], v[84:85] op_sel_hi:[1,0]
	v_pk_mul_f32 v[46:47], v[46:47], v[82:83] op_sel_hi:[1,0]
	v_pk_mul_f32 v[48:49], v[48:49], v[82:83] op_sel_hi:[1,0]
	v_pk_mul_f32 v[34:35], v[34:35], v[66:67] op_sel_hi:[1,0]
	v_pk_mul_f32 v[36:37], v[36:37], v[66:67] op_sel_hi:[1,0]
	v_pk_mul_f32 v[18:19], v[18:19], v[86:87] op_sel_hi:[1,0]
	v_pk_mul_f32 v[20:21], v[20:21], v[86:87] op_sel_hi:[1,0]
	v_pk_mul_f32 v[30:31], v[30:31], v[66:67] op_sel_hi:[1,0]
	v_pk_mul_f32 v[60:61], v[60:61], v[94:95]
	v_pk_mul_f32 v[58:59], v[58:59], v[92:93]
	v_bfe_u32 v98, v60, 16, 1
	v_bfe_u32 v96, v58, 16, 1
	v_bfe_u32 v97, v59, 16, 1
	v_bfe_u32 v99, v61, 16, 1
	v_add3_u32 v58, v58, v96, s19
	v_add3_u32 v60, v60, v98, s19
	v_pk_mul_f32 v[62:63], v[62:63], v[92:93]
	v_add3_u32 v59, v59, v97, s19
	v_add3_u32 v61, v61, v99, s19
	v_lshrrev_b32_e32 v58, 16, v58
	v_lshrrev_b32_e32 v60, 16, v60
	v_bfe_u32 v100, v62, 16, 1
	v_and_or_b32 v58, v59, s62, v58
	v_and_or_b32 v59, v61, s62, v60
	v_add3_u32 v62, v62, v100, s19
	global_store_dwordx2 v[80:81], v[58:59], off
	v_bfe_u32 v58, v63, 16, 1
	v_pk_mul_f32 v[64:65], v[64:65], v[94:95]
	v_lshrrev_b32_e32 v62, 16, v62
	v_add3_u32 v58, v63, v58, s19
	v_and_or_b32 v60, v58, s62, v62
	v_bfe_u32 v58, v64, 16, 1
	v_add3_u32 v58, v64, v58, s19
	v_bfe_u32 v59, v65, 16, 1
	v_lshrrev_b32_e32 v58, 16, v58
	v_add3_u32 v59, v65, v59, s19
	v_and_or_b32 v61, v59, s62, v58
	v_lshl_add_u64 v[58:59], s[52:53], 0, v[74:75]
	v_pk_mul_f32 v[54:55], v[54:55], v[92:93]
	global_store_dwordx2 v[58:59], v[60:61], off offset:-1024
	v_bfe_u32 v60, v54, 16, 1
	v_add3_u32 v54, v54, v60, s19
	v_bfe_u32 v60, v55, 16, 1
	v_pk_mul_f32 v[56:57], v[56:57], v[94:95]
	v_lshrrev_b32_e32 v54, 16, v54
	v_add3_u32 v55, v55, v60, s19
	v_and_or_b32 v60, v55, s62, v54
	v_bfe_u32 v54, v56, 16, 1
	v_pk_mul_f32 v[50:51], v[50:51], v[92:93]
	v_add3_u32 v54, v56, v54, s19
	v_bfe_u32 v56, v50, 16, 1
	v_add3_u32 v50, v50, v56, s19
	v_bfe_u32 v56, v51, 16, 1
	v_pk_mul_f32 v[52:53], v[52:53], v[94:95]
	v_lshrrev_b32_e32 v50, 16, v50
	v_add3_u32 v51, v51, v56, s19
	v_and_or_b32 v56, v51, s62, v50
	v_bfe_u32 v50, v52, 16, 1
	v_bfe_u32 v55, v57, 16, 1
	v_add3_u32 v50, v52, v50, s19
	v_bfe_u32 v51, v53, 16, 1
	v_lshrrev_b32_e32 v54, 16, v54
	v_add3_u32 v55, v57, v55, s19
	v_lshrrev_b32_e32 v50, 16, v50
	v_add3_u32 v51, v53, v51, s19
	v_and_or_b32 v61, v55, s62, v54
	v_lshl_add_u64 v[54:55], s[52:53], 0, v[76:77]
	v_and_or_b32 v57, v51, s62, v50
	v_lshl_add_u64 v[50:51], s[52:53], 0, v[78:79]
	global_store_dwordx2 v[54:55], v[60:61], off offset:-1024
	global_store_dwordx2 v[50:51], v[56:57], off offset:-1024
	s_nop 1
	v_mov_b64_e32 v[60:61], v[124:125]
	v_mov_b64_e32 v[62:63], v[126:127]
	v_pk_mul_f32 v[32:33], v[32:33], v[66:67] op_sel_hi:[1,0]
	v_pk_mul_f32 v[26:27], v[26:27], v[82:83] op_sel_hi:[1,0]
	v_pk_mul_f32 v[28:29], v[28:29], v[82:83] op_sel_hi:[1,0]
	v_pk_mul_f32 v[22:23], v[22:23], v[84:85] op_sel_hi:[1,0]
	v_pk_mul_f32 v[24:25], v[24:25], v[84:85] op_sel_hi:[1,0]
	s_add_i32 s12, s12, s18
	s_add_u32 s46, s46, s28
	s_addc_u32 s47, s47, s29
	s_add_u32 s48, s48, s28
	v_pk_mul_f32 v[2:3], v[2:3], v[86:87] op_sel_hi:[1,0]
	v_pk_mul_f32 v[4:5], v[4:5], v[86:87] op_sel_hi:[1,0]
	s_addc_u32 s49, s49, s29
	v_pk_mul_f32 v[14:15], v[14:15], v[66:67] op_sel_hi:[1,0]
	v_pk_mul_f32 v[16:17], v[16:17], v[66:67] op_sel_hi:[1,0]
	v_pk_mul_f32 v[10:11], v[10:11], v[82:83] op_sel_hi:[1,0]
	v_pk_mul_f32 v[12:13], v[12:13], v[82:83] op_sel_hi:[1,0]
	v_pk_mul_f32 v[6:7], v[6:7], v[84:85] op_sel_hi:[1,0]
	v_pk_mul_f32 v[8:9], v[8:9], v[84:85] op_sel_hi:[1,0]
	s_add_u32 s56, s56, s28
	s_addc_u32 s57, s57, s29
	s_add_u32 s60, s60, s28
	s_addc_u32 s61, s61, s29
	v_lshl_add_u64 v[70:71], v[70:71], 0, s[36:37]
	v_lshl_add_u64 v[72:73], v[72:73], 0, s[44:45]
	v_lshl_add_u64 v[74:75], v[74:75], 0, s[44:45]
	v_lshl_add_u64 v[76:77], v[76:77], 0, s[44:45]
	s_cmpk_gt_i32 s12, 0x3fff
	v_lshl_add_u64 v[78:79], v[78:79], 0, s[44:45]
	v_pk_mul_f32 v[40:41], v[40:41], v[62:63]
	v_pk_mul_f32 v[38:39], v[38:39], v[60:61]
	v_pk_mul_f32 v[44:45], v[44:45], v[62:63]
	v_pk_mul_f32 v[42:43], v[42:43], v[60:61]
	v_bfe_u32 v52, v38, 16, 1
	v_bfe_u32 v56, v40, 16, 1
	v_bfe_u32 v53, v39, 16, 1
	v_bfe_u32 v57, v41, 16, 1
	v_bfe_u32 v64, v42, 16, 1
	v_bfe_u32 v92, v44, 16, 1
	v_add3_u32 v38, v38, v52, s19
	v_add3_u32 v40, v40, v56, s19
	v_bfe_u32 v65, v43, 16, 1
	v_bfe_u32 v93, v45, 16, 1
	v_add3_u32 v39, v39, v53, s19
	v_add3_u32 v41, v41, v57, s19
	v_add3_u32 v42, v42, v64, s19
	v_add3_u32 v44, v44, v92, s19
	v_lshrrev_b32_e32 v38, 16, v38
	v_lshrrev_b32_e32 v40, 16, v40
	v_pk_mul_f32 v[46:47], v[46:47], v[60:61]
	v_add3_u32 v43, v43, v65, s19
	v_add3_u32 v45, v45, v93, s19
	v_lshrrev_b32_e32 v42, 16, v42
	v_lshrrev_b32_e32 v44, 16, v44
	v_and_or_b32 v38, v39, s62, v38
	v_and_or_b32 v39, v41, s62, v40
	v_and_or_b32 v40, v43, s62, v42
	v_and_or_b32 v41, v45, s62, v44
	global_store_dwordx2 v[80:81], v[38:39], off offset:512
	global_store_dwordx2 v[58:59], v[40:41], off offset:-512
	v_bfe_u32 v38, v46, 16, 1
	v_add3_u32 v38, v46, v38, s19
	v_bfe_u32 v39, v47, 16, 1
	v_pk_mul_f32 v[48:49], v[48:49], v[62:63]
	v_lshrrev_b32_e32 v38, 16, v38
	v_add3_u32 v39, v47, v39, s19
	v_and_or_b32 v38, v39, s62, v38
	v_bfe_u32 v39, v48, 16, 1
	v_add3_u32 v39, v48, v39, s19
	v_bfe_u32 v40, v49, 16, 1
	v_lshrrev_b32_e32 v39, 16, v39
	v_add3_u32 v40, v49, v40, s19
	v_and_or_b32 v39, v40, s62, v39
	v_pk_mul_f32 v[34:35], v[34:35], v[60:61]
	global_store_dwordx2 v[54:55], v[38:39], off offset:-512
	v_bfe_u32 v38, v34, 16, 1
	v_add3_u32 v34, v34, v38, s19
	v_bfe_u32 v38, v35, 16, 1
	v_pk_mul_f32 v[36:37], v[36:37], v[62:63]
	v_lshrrev_b32_e32 v34, 16, v34
	v_add3_u32 v35, v35, v38, s19
	v_and_or_b32 v34, v35, s62, v34
	v_bfe_u32 v35, v36, 16, 1
	v_add3_u32 v35, v36, v35, s19
	v_bfe_u32 v36, v37, 16, 1
	v_lshrrev_b32_e32 v35, 16, v35
	v_add3_u32 v36, v37, v36, s19
	v_and_or_b32 v35, v36, s62, v35
	global_store_dwordx2 v[50:51], v[34:35], off offset:-512
	s_nop 1
	v_mov_b64_e32 v[34:35], v[128:129]
	v_mov_b64_e32 v[36:37], v[130:131]
	v_pk_mul_f32 v[20:21], v[20:21], v[36:37]
	v_pk_mul_f32 v[18:19], v[18:19], v[34:35]
	v_pk_mul_f32 v[24:25], v[24:25], v[36:37]
	v_pk_mul_f32 v[22:23], v[22:23], v[34:35]
	v_pk_mul_f32 v[28:29], v[28:29], v[36:37]
	v_pk_mul_f32 v[26:27], v[26:27], v[34:35]
	v_pk_mul_f32 v[32:33], v[32:33], v[36:37]
	v_pk_mul_f32 v[30:31], v[30:31], v[34:35]
	v_bfe_u32 v34, v18, 16, 1
	v_bfe_u32 v36, v20, 16, 1
	v_bfe_u32 v35, v19, 16, 1
	v_bfe_u32 v37, v21, 16, 1
	v_bfe_u32 v38, v22, 16, 1
	v_bfe_u32 v40, v24, 16, 1
	v_bfe_u32 v42, v26, 16, 1
	v_bfe_u32 v44, v28, 16, 1
	v_add3_u32 v18, v18, v34, s19
	v_add3_u32 v20, v20, v36, s19
	v_bfe_u32 v39, v23, 16, 1
	v_bfe_u32 v41, v25, 16, 1
	v_bfe_u32 v43, v27, 16, 1
	v_bfe_u32 v45, v29, 16, 1
	v_add3_u32 v19, v19, v35, s19
	v_add3_u32 v21, v21, v37, s19
	v_add3_u32 v22, v22, v38, s19
	v_add3_u32 v24, v24, v40, s19
	v_add3_u32 v26, v26, v42, s19
	v_add3_u32 v28, v28, v44, s19
	v_lshrrev_b32_e32 v18, 16, v18
	v_lshrrev_b32_e32 v20, 16, v20
	v_add3_u32 v23, v23, v39, s19
	v_add3_u32 v25, v25, v41, s19
	v_add3_u32 v27, v27, v43, s19
	v_add3_u32 v29, v29, v45, s19
	v_lshrrev_b32_e32 v22, 16, v22
	v_lshrrev_b32_e32 v24, 16, v24
	v_lshrrev_b32_e32 v26, 16, v26
	v_lshrrev_b32_e32 v28, 16, v28
	v_and_or_b32 v18, v19, s62, v18
	v_and_or_b32 v19, v21, s62, v20
	v_and_or_b32 v20, v23, s62, v22
	v_and_or_b32 v21, v25, s62, v24
	v_and_or_b32 v22, v27, s62, v26
	v_and_or_b32 v23, v29, s62, v28
	global_store_dwordx2 v[80:81], v[18:19], off offset:1024
	global_store_dwordx2 v[58:59], v[20:21], off
	global_store_dwordx2 v[54:55], v[22:23], off
	v_bfe_u32 v18, v30, 16, 1
	v_add3_u32 v18, v30, v18, s19
	v_bfe_u32 v19, v31, 16, 1
	v_lshrrev_b32_e32 v18, 16, v18
	v_add3_u32 v19, v31, v19, s19
	v_and_or_b32 v18, v19, s62, v18
	v_bfe_u32 v19, v32, 16, 1
	v_add3_u32 v19, v32, v19, s19
	v_bfe_u32 v20, v33, 16, 1
	v_lshrrev_b32_e32 v19, 16, v19
	v_add3_u32 v20, v33, v20, s19
	v_and_or_b32 v19, v20, s62, v19
	global_store_dwordx2 v[50:51], v[18:19], off
	s_nop 1
	v_mov_b64_e32 v[18:19], v[132:133]
	v_mov_b64_e32 v[20:21], v[134:135]
	v_pk_mul_f32 v[4:5], v[4:5], v[20:21]
	v_pk_mul_f32 v[2:3], v[2:3], v[18:19]
	v_pk_mul_f32 v[8:9], v[8:9], v[20:21]
	v_pk_mul_f32 v[6:7], v[6:7], v[18:19]
	v_pk_mul_f32 v[12:13], v[12:13], v[20:21]
	v_pk_mul_f32 v[10:11], v[10:11], v[18:19]
	v_pk_mul_f32 v[16:17], v[16:17], v[20:21]
	v_pk_mul_f32 v[14:15], v[14:15], v[18:19]
	v_bfe_u32 v18, v2, 16, 1
	v_bfe_u32 v20, v4, 16, 1
	v_bfe_u32 v19, v3, 16, 1
	v_bfe_u32 v21, v5, 16, 1
	v_bfe_u32 v22, v6, 16, 1
	v_bfe_u32 v24, v8, 16, 1
	v_bfe_u32 v26, v10, 16, 1
	v_bfe_u32 v28, v12, 16, 1
	v_bfe_u32 v30, v14, 16, 1
	v_bfe_u32 v32, v16, 16, 1
	v_add3_u32 v2, v2, v18, s19
	v_add3_u32 v4, v4, v20, s19
	v_bfe_u32 v23, v7, 16, 1
	v_bfe_u32 v25, v9, 16, 1
	v_bfe_u32 v27, v11, 16, 1
	v_bfe_u32 v29, v13, 16, 1
	v_bfe_u32 v31, v15, 16, 1
	v_bfe_u32 v33, v17, 16, 1
	v_add3_u32 v3, v3, v19, s19
	v_add3_u32 v5, v5, v21, s19
	v_add3_u32 v6, v6, v22, s19
	v_add3_u32 v8, v8, v24, s19
	v_add3_u32 v10, v10, v26, s19
	v_add3_u32 v12, v12, v28, s19
	v_add3_u32 v14, v14, v30, s19
	v_add3_u32 v16, v16, v32, s19
	v_lshrrev_b32_e32 v2, 16, v2
	v_lshrrev_b32_e32 v4, 16, v4
	v_add3_u32 v7, v7, v23, s19
	v_add3_u32 v9, v9, v25, s19
	v_add3_u32 v11, v11, v27, s19
	v_add3_u32 v13, v13, v29, s19
	v_add3_u32 v15, v15, v31, s19
	v_add3_u32 v17, v17, v33, s19
	v_lshrrev_b32_e32 v6, 16, v6
	v_lshrrev_b32_e32 v8, 16, v8
	v_lshrrev_b32_e32 v10, 16, v10
	v_lshrrev_b32_e32 v12, 16, v12
	v_lshrrev_b32_e32 v14, 16, v14
	v_lshrrev_b32_e32 v16, 16, v16
	v_and_or_b32 v2, v3, s62, v2
	v_and_or_b32 v3, v5, s62, v4
	v_and_or_b32 v4, v7, s62, v6
	v_and_or_b32 v5, v9, s62, v8
	v_and_or_b32 v6, v11, s62, v10
	v_and_or_b32 v7, v13, s62, v12
	v_and_or_b32 v8, v15, s62, v14
	v_and_or_b32 v9, v17, s62, v16
	global_store_dwordx2 v[80:81], v[2:3], off offset:1536
	global_store_dwordx2 v[58:59], v[4:5], off offset:512
	global_store_dwordx2 v[54:55], v[6:7], off offset:512
	global_store_dwordx2 v[50:51], v[8:9], off offset:512
	s_cbranch_scc1 .LBB0_58
